# out-proj GEMM steady K-loop rescheduled the same way as the in-proj loop
# speedup vs baseline: 1.2406x; 1.0068x over previous
; template <int EPI>
; DI bool tile_coords(int j, int mpx, int& m0, int& n0) {
;     ...
;   } else {
;     if (q >= mpx * 4) return false;
;     m0 = (x * mpx + (q >> 2)) * 256;
;     n0 = (q & 3) * 256;
;   }
; template <int EPI>
; DI void gemm_phase(const P& p, int l, const u16* __restrict__ A, const u16* __restrict__ Bt, int mpx, char* lds) {
;     ...
;   while (true) {
;   const int tn = t + 1;
;   int m1 = 0, n1 = 0;
;   const bool has_next = tile_coords<EPI>(tn, mpx, m1, n1);
;   const u16* Agn = A + (size_t)m1 * 1024;
;   const u16* Bgn = Bt + (size_t)n1 * 1024;
;   f32x4 acc[8][4];
; #pragma unroll
;   for (int i = 0; i < 8; ++i)
; #pragma unroll
;     for (int j = 0; j < 4; ++j) acc[i][j] = zero4();
;   {
;   const int lane = tid & 63, w = tid >> 6, r = lane & 15, g = lane >> 4, wm = w >> 2, wn = w & 3;
;   __syncthreads();
;   GLOAD(Ag, Bg, 64)
;   __builtin_amdgcn_sched_barrier(0);
;   GCOMPUTE_KS(As0, Bs0, 0)
;   __builtin_amdgcn_sched_barrier(0);
;   GSTORE(As1, Bs1)
;   GLOAD(Ag, Bg, 128)
;   __builtin_amdgcn_sched_barrier(0);
;   GCOMPUTE_KS(As0, Bs0, 1)
.LBB0_69:
	v_lshl_add_u64 v[94:95], s[48:49], 0, v[196:197]
	v_add_co_u32_e32 v96, vcc, s33, v94
	v_lshl_add_u64 v[102:103], s[46:47], 0, v[196:197]
	s_nop 0
	v_addc_co_u32_e32 v97, vcc, 0, v95, vcc
	v_add_co_u32_e32 v98, vcc, s35, v94
	s_waitcnt lgkmcnt(0)
	s_nop 0
	v_addc_co_u32_e32 v99, vcc, 0, v95, vcc
	v_add_co_u32_e32 v100, vcc, s39, v94
	s_barrier
	s_nop 0
	v_addc_co_u32_e32 v101, vcc, 0, v95, vcc
	v_add_co_u32_e32 v104, vcc, s33, v102
	s_nop 1
	v_addc_co_u32_e32 v105, vcc, 0, v103, vcc
	v_add_co_u32_e32 v106, vcc, s35, v102
	global_load_dwordx4 v[2:5], v[94:95], off offset:128
	global_load_dwordx4 v[6:9], v[96:97], off offset:128
	v_addc_co_u32_e32 v107, vcc, 0, v103, vcc
	v_add_co_u32_e32 v110, vcc, s39, v102
	global_load_dwordx4 v[10:13], v[98:99], off offset:128
	global_load_dwordx4 v[14:17], v[100:101], off offset:128
	global_load_dwordx4 v[18:21], v[102:103], off offset:128
	global_load_dwordx4 v[22:25], v[104:105], off offset:128
	v_addc_co_u32_e32 v111, vcc, 0, v103, vcc
	global_load_dwordx4 v[26:29], v[106:107], off offset:128
	global_load_dwordx4 v[30:33], v[110:111], off offset:128
	s_add_i32 s56, s56, 1
	s_mul_i32 s2, s56, s57
	s_add_i32 s2, s2, s84
	s_cmp_ge_u32 s2, s25
	s_cselect_b64 s[40:41], -1, 0
	s_lshr_b32 s42, s2, 2
	s_add_i32 s42, s42, s51
	s_lshl_b32 s58, s42, 8
	s_lshl_b32 s42, s2, 8
	s_and_b32 s59, s42, 0x300
	s_lshl_b32 s42, s59, 11
	s_cmp_lt_u32 s2, s25
	s_cselect_b32 s2, s58, 0
	s_cselect_b32 s44, s42, 0
	s_lshl_b64 s[42:43], s[2:3], 11
	s_add_u32 s42, s16, s42
	s_mov_b32 s64, 1
	s_addc_u32 s43, s17, s43
	ds_read_b128 v[34:37], v227
	ds_read_b128 v[38:41], v207 offset:32768
	ds_read_b128 v[42:45], v207 offset:34816
	ds_read_b128 v[46:49], v227 offset:2048
	ds_read_b128 v[58:61], v207 offset:36864
	ds_read_b128 v[62:65], v207 offset:38912
	ds_read_b128 v[82:85], v227 offset:4096
	ds_read_b128 v[86:89], v227 offset:6144
	s_waitcnt lgkmcnt(6)
	v_mfma_f32_16x16x32_bf16 v[50:53], v[34:37], v[38:41], 0
	s_add_u32 s44, s26, s44
	s_addc_u32 s45, s27, 0
	s_waitcnt lgkmcnt(0)
	v_mfma_f32_16x16x32_bf16 v[126:129], v[86:89], v[38:41], 0
	v_mfma_f32_16x16x32_bf16 v[130:133], v[86:89], v[42:45], 0
	v_mfma_f32_16x16x32_bf16 v[134:137], v[86:89], v[58:61], 0
	v_mfma_f32_16x16x32_bf16 v[138:141], v[86:89], v[62:65], 0
	ds_read_b128 v[86:89], v227 offset:8192
	ds_read_b128 v[90:93], v227 offset:10240
	s_waitcnt lgkmcnt(1)
	v_mfma_f32_16x16x32_bf16 v[142:145], v[86:89], v[38:41], 0
	v_mfma_f32_16x16x32_bf16 v[146:149], v[86:89], v[42:45], 0
	v_mfma_f32_16x16x32_bf16 v[150:153], v[86:89], v[58:61], 0
	v_mfma_f32_16x16x32_bf16 v[154:157], v[86:89], v[62:65], 0
	s_waitcnt lgkmcnt(0)
	v_mfma_f32_16x16x32_bf16 v[158:161], v[90:93], v[38:41], 0
	v_mfma_f32_16x16x32_bf16 v[162:165], v[90:93], v[42:45], 0
	v_mfma_f32_16x16x32_bf16 v[166:169], v[90:93], v[58:61], 0
	v_mfma_f32_16x16x32_bf16 v[170:173], v[90:93], v[62:65], 0
	ds_read_b128 v[86:89], v227 offset:12288
	ds_read_b128 v[90:93], v227 offset:14336
	v_mfma_f32_16x16x32_bf16 v[54:57], v[34:37], v[42:45], 0
	v_mfma_f32_16x16x32_bf16 v[66:69], v[34:37], v[58:61], 0
	v_mfma_f32_16x16x32_bf16 v[34:37], v[34:37], v[62:65], 0
	v_mfma_f32_16x16x32_bf16 v[70:73], v[46:49], v[38:41], 0
	v_mfma_f32_16x16x32_bf16 v[74:77], v[46:49], v[42:45], 0
	v_mfma_f32_16x16x32_bf16 v[78:81], v[46:49], v[58:61], 0
	v_mfma_f32_16x16x32_bf16 v[46:49], v[46:49], v[62:65], 0
	v_mfma_f32_16x16x32_bf16 v[114:117], v[82:85], v[38:41], 0
	v_mfma_f32_16x16x32_bf16 v[118:121], v[82:85], v[42:45], 0
	v_mfma_f32_16x16x32_bf16 v[122:125], v[82:85], v[58:61], 0
	v_mfma_f32_16x16x32_bf16 v[82:85], v[82:85], v[62:65], 0
	s_waitcnt lgkmcnt(1)
	v_mfma_f32_16x16x32_bf16 v[174:177], v[86:89], v[38:41], 0
	v_mfma_f32_16x16x32_bf16 v[178:181], v[86:89], v[42:45], 0
	v_mfma_f32_16x16x32_bf16 v[182:185], v[86:89], v[58:61], 0
	v_mfma_f32_16x16x32_bf16 v[186:189], v[86:89], v[62:65], 0
	s_waitcnt lgkmcnt(0)
	v_mfma_f32_16x16x32_bf16 v[190:193], v[90:93], v[38:41], 0
	v_mfma_f32_16x16x32_bf16 v[212:215], v[90:93], v[42:45], 0
	v_mfma_f32_16x16x32_bf16 v[216:219], v[90:93], v[58:61], 0
	v_mfma_f32_16x16x32_bf16 v[220:223], v[90:93], v[62:65], 0
	s_waitcnt vmcnt(7)
	ds_write_b128 v199, v[2:5]
	s_waitcnt vmcnt(6)
	ds_write_b128 v200, v[6:9]
	s_waitcnt vmcnt(5)
	ds_write_b128 v201, v[10:13]
	s_waitcnt vmcnt(4)
	ds_write_b128 v202, v[14:17]
	s_waitcnt vmcnt(3)
	ds_write_b128 v203, v[18:21]
	s_waitcnt vmcnt(2)
	ds_write_b128 v204, v[22:25]
	s_waitcnt vmcnt(1)
	ds_write_b128 v205, v[26:29]
	s_waitcnt vmcnt(0)
	ds_write_b128 v206, v[30:33]
	global_load_dwordx4 v[18:21], v[94:95], off offset:256
	global_load_dwordx4 v[86:89], v[96:97], off offset:256
	global_load_dwordx4 v[90:93], v[98:99], off offset:256
	s_nop 0
	global_load_dwordx4 v[94:97], v[100:101], off offset:256
	s_nop 0
	global_load_dwordx4 v[98:101], v[102:103], off offset:256
	s_nop 0
	global_load_dwordx4 v[102:105], v[104:105], off offset:256
	s_nop 0
	global_load_dwordx4 v[106:109], v[106:107], off offset:256
	s_nop 0
	global_load_dwordx4 v[110:113], v[110:111], off offset:256
	ds_read_b128 v[2:5], v229
	ds_read_b128 v[234:237], v228 offset:32768
	ds_read_b128 v[238:241], v228 offset:34816
	ds_read_b128 v[242:245], v228 offset:36864
	ds_read_b128 v[246:249], v228 offset:38912
	s_waitcnt lgkmcnt(3)
	v_mfma_f32_16x16x32_bf16 v[6:9], v[2:5], v[234:237], v[50:53]
	s_waitcnt lgkmcnt(2)
	v_mfma_f32_16x16x32_bf16 v[10:13], v[2:5], v[238:241], v[54:57]
	s_waitcnt lgkmcnt(1)
	v_mfma_f32_16x16x32_bf16 v[14:17], v[2:5], v[242:245], v[66:69]
	s_waitcnt lgkmcnt(0)
	v_mfma_f32_16x16x32_bf16 v[22:25], v[2:5], v[246:249], v[34:37]
	ds_read_b128 v[2:5], v229 offset:2048
	s_waitcnt lgkmcnt(0)
; #define GCOMPUTE(AS, BS) GCOMPUTE_KS(AS, BS, 0) GCOMPUTE_KS(AS, BS, 1)
; template <int EPI>
; DI void gemm_phase(const P& p, int l, const u16* __restrict__ A, const u16* __restrict__ Bt, int mpx, char* lds) {
;     ...
;   GCOMPUTE_KS(As0, Bs0, 1)
;   __builtin_amdgcn_sched_barrier(0);
; #pragma unroll 1
;   for (int kk = 1; kk < 15; kk += 2) {
;     __syncthreads();
;     GSTORE(As0, Bs0)
;     GLOAD(Ag, Bg, (kk + 2) * 64)
;     __builtin_amdgcn_sched_barrier(0);
;     GCOMPUTE(As1, Bs1)
;     __builtin_amdgcn_sched_barrier(0);
;     __syncthreads();
;     GSTORE(As1, Bs1)
;     {
;       const bool in_tile = kk + 3 < 16;
;       const u16* pa = in_tile ? Ag : Agn;
;       const u16* pb = in_tile ? Bg : Bgn;
;       const int k0 = in_tile ? (kk + 3) * 64 : 0;
;       GLOAD(pa, pb, k0)
;     }
;     __builtin_amdgcn_sched_barrier(0);
;     GCOMPUTE(As0, Bs0)
	v_mfma_f32_16x16x32_bf16 v[26:29], v[2:5], v[234:237], v[70:73]
	v_mfma_f32_16x16x32_bf16 v[30:33], v[2:5], v[238:241], v[74:77]
	v_mfma_f32_16x16x32_bf16 v[34:37], v[2:5], v[242:245], v[78:81]
	v_mfma_f32_16x16x32_bf16 v[38:41], v[2:5], v[246:249], v[46:49]
	ds_read_b128 v[2:5], v229 offset:4096
	s_waitcnt lgkmcnt(0)
	v_mfma_f32_16x16x32_bf16 v[42:45], v[2:5], v[234:237], v[114:117]
	v_mfma_f32_16x16x32_bf16 v[46:49], v[2:5], v[238:241], v[118:121]
	v_mfma_f32_16x16x32_bf16 v[50:53], v[2:5], v[242:245], v[122:125]
	v_mfma_f32_16x16x32_bf16 v[54:57], v[2:5], v[246:249], v[82:85]
	ds_read_b128 v[2:5], v229 offset:6144
	s_waitcnt lgkmcnt(0)
	v_mfma_f32_16x16x32_bf16 v[58:61], v[2:5], v[234:237], v[126:129]
	v_mfma_f32_16x16x32_bf16 v[62:65], v[2:5], v[238:241], v[130:133]
	v_mfma_f32_16x16x32_bf16 v[66:69], v[2:5], v[242:245], v[134:137]
	v_mfma_f32_16x16x32_bf16 v[70:73], v[2:5], v[246:249], v[138:141]
	ds_read_b128 v[2:5], v229 offset:8192
	s_waitcnt lgkmcnt(0)
	v_mfma_f32_16x16x32_bf16 v[74:77], v[2:5], v[234:237], v[142:145]
	v_mfma_f32_16x16x32_bf16 v[78:81], v[2:5], v[238:241], v[146:149]
	v_mfma_f32_16x16x32_bf16 v[82:85], v[2:5], v[242:245], v[150:153]
	v_mfma_f32_16x16x32_bf16 v[114:117], v[2:5], v[246:249], v[154:157]
	ds_read_b128 v[2:5], v229 offset:10240
	s_waitcnt lgkmcnt(0)
	v_mfma_f32_16x16x32_bf16 v[118:121], v[2:5], v[234:237], v[158:161]
	v_mfma_f32_16x16x32_bf16 v[122:125], v[2:5], v[238:241], v[162:165]
	v_mfma_f32_16x16x32_bf16 v[126:129], v[2:5], v[242:245], v[166:169]
	v_mfma_f32_16x16x32_bf16 v[130:133], v[2:5], v[246:249], v[170:173]
	ds_read_b128 v[2:5], v229 offset:12288
	s_waitcnt lgkmcnt(0)
	v_mfma_f32_16x16x32_bf16 v[134:137], v[2:5], v[234:237], v[174:177]
	v_mfma_f32_16x16x32_bf16 v[138:141], v[2:5], v[238:241], v[178:181]
	v_mfma_f32_16x16x32_bf16 v[142:145], v[2:5], v[242:245], v[182:185]
	v_mfma_f32_16x16x32_bf16 v[146:149], v[2:5], v[246:249], v[186:189]
	ds_read_b128 v[2:5], v229 offset:14336
	s_waitcnt lgkmcnt(0)
	v_mfma_f32_16x16x32_bf16 v[150:153], v[2:5], v[234:237], v[190:193]
	v_mfma_f32_16x16x32_bf16 v[154:157], v[2:5], v[238:241], v[212:215]
	v_mfma_f32_16x16x32_bf16 v[158:161], v[2:5], v[242:245], v[216:219]
	v_mfma_f32_16x16x32_bf16 v[2:5], v[2:5], v[246:249], v[220:223]
	s_movk_i32 s62, 0x100
	s_mov_b64 s[52:53], s[46:47]
	s_mov_b64 s[54:55], s[48:49]
	v_add_u32_e32 v208, s33, v196
	v_add_u32_e32 v209, s35, v196
	v_add_u32_e32 v210, s39, v196
.LBB0_70:
	s_add_i32 s63, s64, 2
	s_barrier
	ds_read_b128 v[212:215], v230
	ds_read_b128 v[216:219], v230 offset:2048
	ds_read_b128 v[220:223], v230 offset:4096
	ds_read_b128 v[234:237], v230 offset:6144
	ds_read_b128 v[238:241], v231
	ds_read_b128 v[242:245], v231 offset:2048
	ds_read_b128 v[246:249], v231 offset:4096
	ds_read_b128 v[250:253], v231 offset:6144
	global_load_dwordx4 v[162:165], v196, s[54:55] offset:384
	global_load_dwordx4 v[166:169], v208, s[54:55] offset:384
	global_load_dwordx4 v[170:173], v209, s[54:55] offset:384
	global_load_dwordx4 v[174:177], v210, s[54:55] offset:384
	global_load_dwordx4 v[178:181], v196, s[52:53] offset:384
	global_load_dwordx4 v[182:185], v208, s[52:53] offset:384
	global_load_dwordx4 v[186:189], v209, s[52:53] offset:384
	global_load_dwordx4 v[190:193], v210, s[52:53] offset:384
	s_waitcnt lgkmcnt(3)
	v_mfma_f32_16x16x32_bf16 v[6:9], v[238:241], v[212:215], v[6:9]
	v_mfma_f32_16x16x32_bf16 v[10:13], v[238:241], v[216:219], v[10:13]
	v_mfma_f32_16x16x32_bf16 v[14:17], v[238:241], v[220:223], v[14:17]
	v_mfma_f32_16x16x32_bf16 v[22:25], v[238:241], v[234:237], v[22:25]
	ds_read_b128 v[238:241], v231 offset:8192
	s_waitcnt vmcnt(15)
	ds_write_b128 v198, v[18:21]
	s_waitcnt lgkmcnt(4)
	v_mfma_f32_16x16x32_bf16 v[26:29], v[242:245], v[212:215], v[26:29]
	v_mfma_f32_16x16x32_bf16 v[30:33], v[242:245], v[216:219], v[30:33]
	v_mfma_f32_16x16x32_bf16 v[34:37], v[242:245], v[220:223], v[34:37]
	v_mfma_f32_16x16x32_bf16 v[38:41], v[242:245], v[234:237], v[38:41]
	ds_read_b128 v[242:245], v231 offset:10240
	s_waitcnt vmcnt(14)
	ds_write_b128 v198, v[86:89] offset:8192
	ds_read_b128 v[18:21], v232
	s_waitcnt lgkmcnt(6)
	v_mfma_f32_16x16x32_bf16 v[42:45], v[246:249], v[212:215], v[42:45]
	v_mfma_f32_16x16x32_bf16 v[46:49], v[246:249], v[216:219], v[46:49]
	v_mfma_f32_16x16x32_bf16 v[50:53], v[246:249], v[220:223], v[50:53]
	v_mfma_f32_16x16x32_bf16 v[54:57], v[246:249], v[234:237], v[54:57]
	ds_read_b128 v[246:249], v231 offset:12288
	s_waitcnt vmcnt(13)
	ds_write_b128 v198, v[90:93] offset:16384
	ds_read_b128 v[86:89], v232 offset:2048
	s_waitcnt lgkmcnt(8)
	v_mfma_f32_16x16x32_bf16 v[58:61], v[250:253], v[212:215], v[58:61]
	v_mfma_f32_16x16x32_bf16 v[62:65], v[250:253], v[216:219], v[62:65]
	v_mfma_f32_16x16x32_bf16 v[66:69], v[250:253], v[220:223], v[66:69]
	v_mfma_f32_16x16x32_bf16 v[70:73], v[250:253], v[234:237], v[70:73]
	ds_read_b128 v[250:253], v231 offset:14336
	s_waitcnt vmcnt(12)
	ds_write_b128 v198, v[94:97] offset:24576
	ds_read_b128 v[90:93], v232 offset:4096
	s_waitcnt lgkmcnt(10)
	v_mfma_f32_16x16x32_bf16 v[74:77], v[238:241], v[212:215], v[74:77]
	v_mfma_f32_16x16x32_bf16 v[78:81], v[238:241], v[216:219], v[78:81]
	v_mfma_f32_16x16x32_bf16 v[82:85], v[238:241], v[220:223], v[82:85]
	v_mfma_f32_16x16x32_bf16 v[114:117], v[238:241], v[234:237], v[114:117]
	ds_read_b128 v[238:241], v233
	s_waitcnt vmcnt(11)
	ds_write_b128 v198, v[98:101] offset:32768
	ds_read_b128 v[94:97], v232 offset:6144
	s_waitcnt lgkmcnt(11)
	v_mfma_f32_16x16x32_bf16 v[118:121], v[242:245], v[212:215], v[118:121]
	v_mfma_f32_16x16x32_bf16 v[122:125], v[242:245], v[216:219], v[122:125]
	v_mfma_f32_16x16x32_bf16 v[126:129], v[242:245], v[220:223], v[126:129]
	v_mfma_f32_16x16x32_bf16 v[130:133], v[242:245], v[234:237], v[130:133]
	ds_read_b128 v[242:245], v233 offset:2048
	s_waitcnt vmcnt(10)
; #define GCOMPUTE(AS, BS) GCOMPUTE_KS(AS, BS, 0) GCOMPUTE_KS(AS, BS, 1)
; template <int EPI>
; DI void gemm_phase(const P& p, int l, const u16* __restrict__ A, const u16* __restrict__ Bt, int mpx, char* lds) {
;     ...
;   for (int kk = 1; kk < 15; kk += 2) {
;     __syncthreads();
;     GSTORE(As0, Bs0)
;     GLOAD(Ag, Bg, (kk + 2) * 64)
;     __builtin_amdgcn_sched_barrier(0);
;     GCOMPUTE(As1, Bs1)
;     __builtin_amdgcn_sched_barrier(0);
;     __syncthreads();
;     GSTORE(As1, Bs1)
;     {
;       const bool in_tile = kk + 3 < 16;
;       const u16* pa = in_tile ? Ag : Agn;
;       const u16* pb = in_tile ? Bg : Bgn;
;       const int k0 = in_tile ? (kk + 3) * 64 : 0;
;       GLOAD(pa, pb, k0)
;     }
;     __builtin_amdgcn_sched_barrier(0);
;     GCOMPUTE(As0, Bs0)
	ds_write_b128 v198, v[102:105] offset:40960
	s_waitcnt lgkmcnt(10)
	v_mfma_f32_16x16x32_bf16 v[134:137], v[246:249], v[212:215], v[134:137]
	v_mfma_f32_16x16x32_bf16 v[138:141], v[246:249], v[216:219], v[138:141]
	v_mfma_f32_16x16x32_bf16 v[142:145], v[246:249], v[220:223], v[142:145]
	v_mfma_f32_16x16x32_bf16 v[146:149], v[246:249], v[234:237], v[146:149]
	ds_read_b128 v[246:249], v233 offset:4096
	s_waitcnt vmcnt(9)
	ds_write_b128 v198, v[106:109] offset:49152
	s_waitcnt lgkmcnt(9)
	v_mfma_f32_16x16x32_bf16 v[150:153], v[250:253], v[212:215], v[150:153]
	v_mfma_f32_16x16x32_bf16 v[154:157], v[250:253], v[216:219], v[154:157]
	v_mfma_f32_16x16x32_bf16 v[158:161], v[250:253], v[220:223], v[158:161]
	v_mfma_f32_16x16x32_bf16 v[2:5], v[250:253], v[234:237], v[2:5]
	ds_read_b128 v[250:253], v233 offset:6144
	s_waitcnt vmcnt(8)
	ds_write_b128 v198, v[110:113] offset:57344
	s_waitcnt lgkmcnt(6)
	v_mfma_f32_16x16x32_bf16 v[6:9], v[238:241], v[18:21], v[6:9]
	v_mfma_f32_16x16x32_bf16 v[10:13], v[238:241], v[86:89], v[10:13]
	v_mfma_f32_16x16x32_bf16 v[14:17], v[238:241], v[90:93], v[14:17]
	v_mfma_f32_16x16x32_bf16 v[22:25], v[238:241], v[94:97], v[22:25]
	ds_read_b128 v[238:241], v233 offset:8192
	s_waitcnt lgkmcnt(6)
	v_mfma_f32_16x16x32_bf16 v[26:29], v[242:245], v[18:21], v[26:29]
	v_mfma_f32_16x16x32_bf16 v[30:33], v[242:245], v[86:89], v[30:33]
	v_mfma_f32_16x16x32_bf16 v[34:37], v[242:245], v[90:93], v[34:37]
	v_mfma_f32_16x16x32_bf16 v[38:41], v[242:245], v[94:97], v[38:41]
	ds_read_b128 v[242:245], v233 offset:10240
	s_waitcnt lgkmcnt(5)
	v_mfma_f32_16x16x32_bf16 v[42:45], v[246:249], v[18:21], v[42:45]
	v_mfma_f32_16x16x32_bf16 v[46:49], v[246:249], v[86:89], v[46:49]
	v_mfma_f32_16x16x32_bf16 v[50:53], v[246:249], v[90:93], v[50:53]
	v_mfma_f32_16x16x32_bf16 v[54:57], v[246:249], v[94:97], v[54:57]
	ds_read_b128 v[246:249], v233 offset:12288
	s_waitcnt lgkmcnt(4)
	v_mfma_f32_16x16x32_bf16 v[58:61], v[250:253], v[18:21], v[58:61]
	v_mfma_f32_16x16x32_bf16 v[62:65], v[250:253], v[86:89], v[62:65]
	v_mfma_f32_16x16x32_bf16 v[66:69], v[250:253], v[90:93], v[66:69]
	v_mfma_f32_16x16x32_bf16 v[70:73], v[250:253], v[94:97], v[70:73]
	ds_read_b128 v[250:253], v233 offset:14336
	s_waitcnt lgkmcnt(3)
	v_mfma_f32_16x16x32_bf16 v[74:77], v[238:241], v[18:21], v[74:77]
	v_mfma_f32_16x16x32_bf16 v[78:81], v[238:241], v[86:89], v[78:81]
	v_mfma_f32_16x16x32_bf16 v[82:85], v[238:241], v[90:93], v[82:85]
	v_mfma_f32_16x16x32_bf16 v[114:117], v[238:241], v[94:97], v[114:117]
	s_waitcnt lgkmcnt(2)
	v_mfma_f32_16x16x32_bf16 v[118:121], v[242:245], v[18:21], v[118:121]
	v_mfma_f32_16x16x32_bf16 v[122:125], v[242:245], v[86:89], v[122:125]
	v_mfma_f32_16x16x32_bf16 v[126:129], v[242:245], v[90:93], v[126:129]
	v_mfma_f32_16x16x32_bf16 v[130:133], v[242:245], v[94:97], v[130:133]
	s_waitcnt lgkmcnt(1)
	v_mfma_f32_16x16x32_bf16 v[134:137], v[246:249], v[18:21], v[134:137]
	v_mfma_f32_16x16x32_bf16 v[138:141], v[246:249], v[86:89], v[138:141]
	v_mfma_f32_16x16x32_bf16 v[142:145], v[246:249], v[90:93], v[142:145]
	v_mfma_f32_16x16x32_bf16 v[146:149], v[246:249], v[94:97], v[146:149]
	s_waitcnt lgkmcnt(0)
	v_mfma_f32_16x16x32_bf16 v[150:153], v[250:253], v[18:21], v[150:153]
	v_mfma_f32_16x16x32_bf16 v[154:157], v[250:253], v[86:89], v[154:157]
	v_mfma_f32_16x16x32_bf16 v[158:161], v[250:253], v[90:93], v[158:161]
	v_mfma_f32_16x16x32_bf16 v[2:5], v[250:253], v[94:97], v[2:5]
	s_waitcnt lgkmcnt(0)
	s_cmp_lt_u32 s64, 13
	s_cselect_b64 s[66:67], -1, 0
	s_and_b64 s[66:67], s[66:67], exec
	s_cselect_b32 s2, s62, 0
	s_cselect_b32 s65, s49, s43
	s_cselect_b32 s68, s48, s42
	s_cselect_b32 s70, s47, s45
	s_cselect_b32 s71, s46, s44
	s_lshl_b64 s[66:67], s[2:3], 1
	s_add_u32 s68, s68, s66
	s_addc_u32 s69, s65, s67
	s_add_u32 s66, s71, s66
	s_addc_u32 s67, s70, s67
	s_barrier
	ds_read_b128 v[212:215], v207 offset:32768
	ds_read_b128 v[216:219], v207 offset:34816
	ds_read_b128 v[220:223], v207 offset:36864
	ds_read_b128 v[234:237], v207 offset:38912
	ds_read_b128 v[238:241], v227
	ds_read_b128 v[242:245], v227 offset:2048
	ds_read_b128 v[246:249], v227 offset:4096
	ds_read_b128 v[250:253], v227 offset:6144
	global_load_dwordx4 v[18:21], v196, s[68:69]
	global_load_dwordx4 v[86:89], v208, s[68:69]
	global_load_dwordx4 v[90:93], v209, s[68:69]
	global_load_dwordx4 v[94:97], v210, s[68:69]
	global_load_dwordx4 v[98:101], v196, s[66:67]
	global_load_dwordx4 v[102:105], v208, s[66:67]
	global_load_dwordx4 v[106:109], v209, s[66:67]
	global_load_dwordx4 v[110:113], v210, s[66:67]
	s_waitcnt lgkmcnt(3)
	v_mfma_f32_16x16x32_bf16 v[6:9], v[238:241], v[212:215], v[6:9]
	v_mfma_f32_16x16x32_bf16 v[10:13], v[238:241], v[216:219], v[10:13]
	v_mfma_f32_16x16x32_bf16 v[14:17], v[238:241], v[220:223], v[14:17]
	v_mfma_f32_16x16x32_bf16 v[22:25], v[238:241], v[234:237], v[22:25]
	ds_read_b128 v[238:241], v227 offset:8192
	s_waitcnt vmcnt(15)
	ds_write_b128 v199, v[162:165]
	s_waitcnt lgkmcnt(4)
	v_mfma_f32_16x16x32_bf16 v[26:29], v[242:245], v[212:215], v[26:29]
	v_mfma_f32_16x16x32_bf16 v[30:33], v[242:245], v[216:219], v[30:33]
	v_mfma_f32_16x16x32_bf16 v[34:37], v[242:245], v[220:223], v[34:37]
	v_mfma_f32_16x16x32_bf16 v[38:41], v[242:245], v[234:237], v[38:41]
	ds_read_b128 v[242:245], v227 offset:10240
	s_waitcnt vmcnt(14)
	ds_write_b128 v200, v[166:169]
	ds_read_b128 v[162:165], v228 offset:32768
	s_waitcnt lgkmcnt(6)
	v_mfma_f32_16x16x32_bf16 v[42:45], v[246:249], v[212:215], v[42:45]
	v_mfma_f32_16x16x32_bf16 v[46:49], v[246:249], v[216:219], v[46:49]
	v_mfma_f32_16x16x32_bf16 v[50:53], v[246:249], v[220:223], v[50:53]
	v_mfma_f32_16x16x32_bf16 v[54:57], v[246:249], v[234:237], v[54:57]
	ds_read_b128 v[246:249], v227 offset:12288
	s_waitcnt vmcnt(13)
; #define GCOMPUTE(AS, BS) GCOMPUTE_KS(AS, BS, 0) GCOMPUTE_KS(AS, BS, 1)
; template <int EPI>
; DI void gemm_phase(const P& p, int l, const u16* __restrict__ A, const u16* __restrict__ Bt, int mpx, char* lds) {
;     ...
;   for (int kk = 1; kk < 15; kk += 2) {
;     __syncthreads();
;     GSTORE(As0, Bs0)
;     GLOAD(Ag, Bg, (kk + 2) * 64)
;     __builtin_amdgcn_sched_barrier(0);
;     GCOMPUTE(As1, Bs1)
;     __builtin_amdgcn_sched_barrier(0);
;     __syncthreads();
;     GSTORE(As1, Bs1)
;     {
;       const bool in_tile = kk + 3 < 16;
;       const u16* pa = in_tile ? Ag : Agn;
;       const u16* pb = in_tile ? Bg : Bgn;
;       const int k0 = in_tile ? (kk + 3) * 64 : 0;
;       GLOAD(pa, pb, k0)
;     }
;     __builtin_amdgcn_sched_barrier(0);
;     GCOMPUTE(As0, Bs0)
;     __builtin_amdgcn_sched_barrier(0);
;   }
	ds_write_b128 v201, v[170:173]
	ds_read_b128 v[166:169], v228 offset:34816
	s_waitcnt lgkmcnt(8)
	v_mfma_f32_16x16x32_bf16 v[58:61], v[250:253], v[212:215], v[58:61]
	v_mfma_f32_16x16x32_bf16 v[62:65], v[250:253], v[216:219], v[62:65]
	v_mfma_f32_16x16x32_bf16 v[66:69], v[250:253], v[220:223], v[66:69]
	v_mfma_f32_16x16x32_bf16 v[70:73], v[250:253], v[234:237], v[70:73]
	ds_read_b128 v[250:253], v227 offset:14336
	s_waitcnt vmcnt(12)
	ds_write_b128 v202, v[174:177]
	ds_read_b128 v[170:173], v228 offset:36864
	s_waitcnt lgkmcnt(10)
	v_mfma_f32_16x16x32_bf16 v[74:77], v[238:241], v[212:215], v[74:77]
	v_mfma_f32_16x16x32_bf16 v[78:81], v[238:241], v[216:219], v[78:81]
	v_mfma_f32_16x16x32_bf16 v[82:85], v[238:241], v[220:223], v[82:85]
	v_mfma_f32_16x16x32_bf16 v[114:117], v[238:241], v[234:237], v[114:117]
	ds_read_b128 v[238:241], v229
	s_waitcnt vmcnt(11)
	ds_write_b128 v203, v[178:181]
	ds_read_b128 v[174:177], v228 offset:38912
	s_waitcnt lgkmcnt(11)
	v_mfma_f32_16x16x32_bf16 v[118:121], v[242:245], v[212:215], v[118:121]
	v_mfma_f32_16x16x32_bf16 v[122:125], v[242:245], v[216:219], v[122:125]
	v_mfma_f32_16x16x32_bf16 v[126:129], v[242:245], v[220:223], v[126:129]
	v_mfma_f32_16x16x32_bf16 v[130:133], v[242:245], v[234:237], v[130:133]
	ds_read_b128 v[242:245], v229 offset:2048
	s_waitcnt vmcnt(10)
	ds_write_b128 v204, v[182:185]
	s_waitcnt lgkmcnt(10)
	v_mfma_f32_16x16x32_bf16 v[134:137], v[246:249], v[212:215], v[134:137]
	v_mfma_f32_16x16x32_bf16 v[138:141], v[246:249], v[216:219], v[138:141]
	v_mfma_f32_16x16x32_bf16 v[142:145], v[246:249], v[220:223], v[142:145]
	v_mfma_f32_16x16x32_bf16 v[146:149], v[246:249], v[234:237], v[146:149]
	ds_read_b128 v[246:249], v229 offset:4096
	s_waitcnt vmcnt(9)
	ds_write_b128 v205, v[186:189]
	s_waitcnt lgkmcnt(9)
	v_mfma_f32_16x16x32_bf16 v[150:153], v[250:253], v[212:215], v[150:153]
	v_mfma_f32_16x16x32_bf16 v[154:157], v[250:253], v[216:219], v[154:157]
	v_mfma_f32_16x16x32_bf16 v[158:161], v[250:253], v[220:223], v[158:161]
	v_mfma_f32_16x16x32_bf16 v[2:5], v[250:253], v[234:237], v[2:5]
	ds_read_b128 v[250:253], v229 offset:6144
	s_waitcnt vmcnt(8)
	ds_write_b128 v206, v[190:193]
	s_waitcnt lgkmcnt(6)
	v_mfma_f32_16x16x32_bf16 v[6:9], v[238:241], v[162:165], v[6:9]
	v_mfma_f32_16x16x32_bf16 v[10:13], v[238:241], v[166:169], v[10:13]
	v_mfma_f32_16x16x32_bf16 v[14:17], v[238:241], v[170:173], v[14:17]
	v_mfma_f32_16x16x32_bf16 v[22:25], v[238:241], v[174:177], v[22:25]
	ds_read_b128 v[238:241], v229 offset:8192
	s_waitcnt lgkmcnt(6)
	v_mfma_f32_16x16x32_bf16 v[26:29], v[242:245], v[162:165], v[26:29]
	v_mfma_f32_16x16x32_bf16 v[30:33], v[242:245], v[166:169], v[30:33]
	v_mfma_f32_16x16x32_bf16 v[34:37], v[242:245], v[170:173], v[34:37]
	v_mfma_f32_16x16x32_bf16 v[38:41], v[242:245], v[174:177], v[38:41]
	ds_read_b128 v[242:245], v229 offset:10240
	s_waitcnt lgkmcnt(5)
	v_mfma_f32_16x16x32_bf16 v[42:45], v[246:249], v[162:165], v[42:45]
	v_mfma_f32_16x16x32_bf16 v[46:49], v[246:249], v[166:169], v[46:49]
	v_mfma_f32_16x16x32_bf16 v[50:53], v[246:249], v[170:173], v[50:53]
	v_mfma_f32_16x16x32_bf16 v[54:57], v[246:249], v[174:177], v[54:57]
	ds_read_b128 v[246:249], v229 offset:12288
	s_waitcnt lgkmcnt(4)
	v_mfma_f32_16x16x32_bf16 v[58:61], v[250:253], v[162:165], v[58:61]
	v_mfma_f32_16x16x32_bf16 v[62:65], v[250:253], v[166:169], v[62:65]
	v_mfma_f32_16x16x32_bf16 v[66:69], v[250:253], v[170:173], v[66:69]
	v_mfma_f32_16x16x32_bf16 v[70:73], v[250:253], v[174:177], v[70:73]
	ds_read_b128 v[250:253], v229 offset:14336
	s_waitcnt lgkmcnt(3)
	v_mfma_f32_16x16x32_bf16 v[74:77], v[238:241], v[162:165], v[74:77]
	v_mfma_f32_16x16x32_bf16 v[78:81], v[238:241], v[166:169], v[78:81]
	v_mfma_f32_16x16x32_bf16 v[82:85], v[238:241], v[170:173], v[82:85]
	v_mfma_f32_16x16x32_bf16 v[114:117], v[238:241], v[174:177], v[114:117]
	s_waitcnt lgkmcnt(2)
	v_mfma_f32_16x16x32_bf16 v[118:121], v[242:245], v[162:165], v[118:121]
	v_mfma_f32_16x16x32_bf16 v[122:125], v[242:245], v[166:169], v[122:125]
	v_mfma_f32_16x16x32_bf16 v[126:129], v[242:245], v[170:173], v[126:129]
	v_mfma_f32_16x16x32_bf16 v[130:133], v[242:245], v[174:177], v[130:133]
	s_waitcnt lgkmcnt(1)
	v_mfma_f32_16x16x32_bf16 v[134:137], v[246:249], v[162:165], v[134:137]
	v_mfma_f32_16x16x32_bf16 v[138:141], v[246:249], v[166:169], v[138:141]
	v_mfma_f32_16x16x32_bf16 v[142:145], v[246:249], v[170:173], v[142:145]
	v_mfma_f32_16x16x32_bf16 v[146:149], v[246:249], v[174:177], v[146:149]
	s_waitcnt lgkmcnt(0)
	v_mfma_f32_16x16x32_bf16 v[150:153], v[250:253], v[162:165], v[150:153]
	v_mfma_f32_16x16x32_bf16 v[154:157], v[250:253], v[166:169], v[154:157]
	v_mfma_f32_16x16x32_bf16 v[158:161], v[250:253], v[170:173], v[158:161]
	v_mfma_f32_16x16x32_bf16 v[2:5], v[250:253], v[174:177], v[2:5]
	s_waitcnt lgkmcnt(0)
	s_addk_i32 s62, 0x80
	s_add_u32 s54, s54, 0x100
	s_addc_u32 s55, s55, 0
	s_add_u32 s52, s52, 0x100
	s_addc_u32 s53, s53, 0
	s_cmp_gt_u32 s64, 12
	s_mov_b32 s64, s63
	s_cbranch_scc0 .LBB0_70
	s_barrier
; #define GCOMPUTE(AS, BS) GCOMPUTE_KS(AS, BS, 0) GCOMPUTE_KS(AS, BS, 1)
; template <int EPI>
; DI void gemm_phase(const P& p, int l, const u16* __restrict__ A, const u16* __restrict__ Bt, int mpx, char* lds) {
;     ...
;   __syncthreads();
;   __builtin_amdgcn_sched_barrier(0);
;   GCOMPUTE(As1, Bs1)
;   __builtin_amdgcn_sched_barrier(0);
	ds_read_b128 v[162:165], v231
	ds_read_b128 v[166:169], v230
	ds_read_b128 v[170:173], v230 offset:2048
	ds_read_b128 v[174:177], v230 offset:4096
	ds_read_b128 v[178:181], v230 offset:6144
	s_waitcnt lgkmcnt(3)
	v_mfma_f32_16x16x32_bf16 v[6:9], v[162:165], v[166:169], v[6:9]
	s_waitcnt lgkmcnt(2)
	v_mfma_f32_16x16x32_bf16 v[10:13], v[162:165], v[170:173], v[10:13]
	s_waitcnt lgkmcnt(1)
	v_mfma_f32_16x16x32_bf16 v[14:17], v[162:165], v[174:177], v[14:17]
	s_waitcnt lgkmcnt(0)
	v_mfma_f32_16x16x32_bf16 v[22:25], v[162:165], v[178:181], v[22:25]
	ds_read_b128 v[162:165], v231 offset:2048
	s_waitcnt lgkmcnt(0)
	v_mfma_f32_16x16x32_bf16 v[26:29], v[162:165], v[166:169], v[26:29]
	v_mfma_f32_16x16x32_bf16 v[30:33], v[162:165], v[170:173], v[30:33]
	v_mfma_f32_16x16x32_bf16 v[34:37], v[162:165], v[174:177], v[34:37]
	v_mfma_f32_16x16x32_bf16 v[38:41], v[162:165], v[178:181], v[38:41]
	ds_read_b128 v[162:165], v231 offset:4096
	s_waitcnt lgkmcnt(0)
	v_mfma_f32_16x16x32_bf16 v[42:45], v[162:165], v[166:169], v[42:45]
	v_mfma_f32_16x16x32_bf16 v[46:49], v[162:165], v[170:173], v[46:49]
	v_mfma_f32_16x16x32_bf16 v[50:53], v[162:165], v[174:177], v[50:53]
	v_mfma_f32_16x16x32_bf16 v[54:57], v[162:165], v[178:181], v[54:57]
	ds_read_b128 v[162:165], v231 offset:6144
	s_waitcnt lgkmcnt(0)
	v_mfma_f32_16x16x32_bf16 v[58:61], v[162:165], v[166:169], v[58:61]
	v_mfma_f32_16x16x32_bf16 v[62:65], v[162:165], v[170:173], v[62:65]
	v_mfma_f32_16x16x32_bf16 v[66:69], v[162:165], v[174:177], v[66:69]
	v_mfma_f32_16x16x32_bf16 v[162:165], v[162:165], v[178:181], v[70:73]
	s_nop 2
	ds_read_b128 v[70:73], v231 offset:8192
	s_waitcnt lgkmcnt(0)
	v_mfma_f32_16x16x32_bf16 v[182:185], v[70:73], v[166:169], v[74:77]
	s_nop 2
	ds_read_b128 v[74:77], v233
	v_mfma_f32_16x16x32_bf16 v[186:189], v[70:73], v[170:173], v[78:81]
	v_mfma_f32_16x16x32_bf16 v[190:193], v[70:73], v[174:177], v[82:85]
	v_mfma_f32_16x16x32_bf16 v[212:215], v[70:73], v[178:181], v[114:117]
	ds_read_b128 v[70:73], v231 offset:10240
	s_waitcnt lgkmcnt(0)
	v_mfma_f32_16x16x32_bf16 v[216:219], v[70:73], v[166:169], v[118:121]
	v_mfma_f32_16x16x32_bf16 v[220:223], v[70:73], v[170:173], v[122:125]
	v_mfma_f32_16x16x32_bf16 v[234:237], v[70:73], v[174:177], v[126:129]
	v_mfma_f32_16x16x32_bf16 v[238:241], v[70:73], v[178:181], v[130:133]
	ds_read_b128 v[70:73], v231 offset:12288
	s_waitcnt lgkmcnt(0)
	v_mfma_f32_16x16x32_bf16 v[242:245], v[70:73], v[166:169], v[134:137]
	v_mfma_f32_16x16x32_bf16 v[246:249], v[70:73], v[170:173], v[138:141]
	v_mfma_f32_16x16x32_bf16 v[250:253], v[70:73], v[174:177], v[142:145]
	v_mfma_f32_16x16x32_bf16 v[208:211], v[70:73], v[178:181], v[146:149]
	ds_read_b128 v[70:73], v231 offset:14336
	s_waitcnt lgkmcnt(0)
	v_mfma_f32_16x16x32_bf16 v[178:181], v[70:73], v[178:181], v[2:5]
	s_nop 2
	ds_read_b128 v[2:5], v232
	s_waitcnt lgkmcnt(0)
	v_mfma_f32_16x16x32_bf16 v[146:149], v[74:77], v[2:5], v[6:9]
	s_nop 2
	ds_read_b128 v[6:9], v232 offset:2048
	v_mfma_f32_16x16x32_bf16 v[170:173], v[70:73], v[170:173], v[154:157]
	s_waitcnt lgkmcnt(0)
	v_mfma_f32_16x16x32_bf16 v[154:157], v[74:77], v[6:9], v[10:13]
	s_nop 2
	ds_read_b128 v[10:13], v232 offset:4096
	v_mfma_f32_16x16x32_bf16 v[166:169], v[70:73], v[166:169], v[150:153]
	s_waitcnt lgkmcnt(0)
	v_mfma_f32_16x16x32_bf16 v[150:153], v[74:77], v[10:13], v[14:17]
	s_nop 2
	ds_read_b128 v[14:17], v232 offset:6144
	v_mfma_f32_16x16x32_bf16 v[174:177], v[70:73], v[174:177], v[158:161]
	s_waitcnt lgkmcnt(0)
	v_mfma_f32_16x16x32_bf16 v[158:161], v[74:77], v[14:17], v[22:25]
	s_nop 2
	ds_read_b128 v[22:25], v233 offset:2048
	s_waitcnt lgkmcnt(0)
	v_mfma_f32_16x16x32_bf16 v[138:141], v[22:25], v[2:5], v[26:29]
	s_nop 2
	ds_read_b128 v[26:29], v233 offset:12288
	v_mfma_f32_16x16x32_bf16 v[142:145], v[22:25], v[6:9], v[30:33]
	v_mfma_f32_16x16x32_bf16 v[130:133], v[22:25], v[10:13], v[34:37]
	v_mfma_f32_16x16x32_bf16 v[134:137], v[22:25], v[14:17], v[38:41]
	ds_read_b128 v[22:25], v233 offset:4096
	s_waitcnt lgkmcnt(0)
	v_mfma_f32_16x16x32_bf16 v[122:125], v[22:25], v[2:5], v[42:45]
	v_mfma_f32_16x16x32_bf16 v[126:129], v[22:25], v[6:9], v[46:49]
	v_mfma_f32_16x16x32_bf16 v[114:117], v[22:25], v[10:13], v[50:53]
	v_mfma_f32_16x16x32_bf16 v[118:121], v[22:25], v[14:17], v[54:57]
	ds_read_b128 v[22:25], v233 offset:6144
	s_waitcnt lgkmcnt(0)
	v_mfma_f32_16x16x32_bf16 v[78:81], v[22:25], v[2:5], v[58:61]
	v_mfma_f32_16x16x32_bf16 v[82:85], v[22:25], v[6:9], v[62:65]
	v_mfma_f32_16x16x32_bf16 v[70:73], v[22:25], v[10:13], v[66:69]
	v_mfma_f32_16x16x32_bf16 v[74:77], v[22:25], v[14:17], v[162:165]
	ds_read_b128 v[22:25], v233 offset:8192
	s_nop 1
	ds_read_b128 v[162:165], v233 offset:14336
	s_waitcnt lgkmcnt(1)
	v_mfma_f32_16x16x32_bf16 v[62:65], v[22:25], v[2:5], v[182:185]
	v_mfma_f32_16x16x32_bf16 v[66:69], v[22:25], v[6:9], v[186:189]
	v_mfma_f32_16x16x32_bf16 v[54:57], v[22:25], v[10:13], v[190:193]
	v_mfma_f32_16x16x32_bf16 v[58:61], v[22:25], v[14:17], v[212:215]
	ds_read_b128 v[22:25], v233 offset:10240
	s_waitcnt lgkmcnt(0)
	v_mfma_f32_16x16x32_bf16 v[46:49], v[22:25], v[2:5], v[216:219]
	v_mfma_f32_16x16x32_bf16 v[50:53], v[22:25], v[6:9], v[220:223]
	v_mfma_f32_16x16x32_bf16 v[38:41], v[22:25], v[10:13], v[234:237]
	v_mfma_f32_16x16x32_bf16 v[42:45], v[22:25], v[14:17], v[238:241]
	v_mfma_f32_16x16x32_bf16 v[30:33], v[26:29], v[2:5], v[242:245]
	v_mfma_f32_16x16x32_bf16 v[34:37], v[26:29], v[6:9], v[246:249]
	v_mfma_f32_16x16x32_bf16 v[22:25], v[26:29], v[10:13], v[250:253]
	v_mfma_f32_16x16x32_bf16 v[26:29], v[26:29], v[14:17], v[208:211]
	v_mfma_f32_16x16x32_bf16 v[166:169], v[162:165], v[2:5], v[166:169]
	v_mfma_f32_16x16x32_bf16 v[170:173], v[162:165], v[6:9], v[170:173]
	v_mfma_f32_16x16x32_bf16 v[2:5], v[162:165], v[10:13], v[174:177]
	v_mfma_f32_16x16x32_bf16 v[6:9], v[162:165], v[14:17], v[178:181]
	v_mov_b32_e32 v14, v195
	s_barrier
; DI int tidx() { int t = threadIdx.x; asm volatile("" : "+v"(t)); return t; }
; template <int EPI>
; DI void gemm_phase(const P& p, int l, const u16* __restrict__ A, const u16* __restrict__ Bt, int mpx, char* lds) {
;     ...
;   __syncthreads();
;   GSTORE(As0, Bs0)
;   const int tid_e = tidx();
;   const int lane = tid_e & 63, w = tid_e >> 6, r = lane & 15, g = lane >> 4, wm = w >> 2, wn = w & 3;
;   if constexpr (EPI == 1) {
;     const float alpha = 1.4142135623730951f;
;     float* Cw = (float*)(lds + 65536) + w * (16 * 68);
;     const int mr = m0 < MLAT ? (m0 >> 11) : 16;
;     const int colw = n0 + wn * 64;
;     const float* gate = p.mod + (size_t)(l * 17 + mr) * 3072 + 2048 + colw;
;     const float* xr = ((l == 0) ? (m0 < MLAT ? p.x + (size_t)m0 * 1024 : p.ctx + (size_t)(m0 - MLAT) * 1024)
;                                 : p.out + (size_t)m0 * 1024) + (size_t)(wm * 128) * 1024 + colw;
;     float* Z = (float*)p.slab + (size_t)(m0 + wm * 128) * 1024 + colw;
;     const int c4 = (lane & 15) * 4, rr0 = lane >> 4;
;     const float4 gt = *(const float4*)(gate + c4);
;     float4 xn[4];
; #pragma unroll
;     for (int i = 0; i < 4; ++i) xn[i] = *(const float4*)(xr + (size_t)(rr0 + 4 * i) * 1024 + c4);
; #pragma unroll
;     for (int mi = 0; mi < 8; ++mi) {
;       float4 xv[4];
; #pragma unroll
;       for (int i = 0; i < 4; ++i) xv[i] = xn[i];
;       if (mi < 7) {
; #pragma unroll
;         for (int i = 0; i < 4; ++i) xn[i] = *(const float4*)(xr + (size_t)((mi + 1) * 16 + rr0 + 4 * i) * 1024 + c4);
;       }
; #pragma unroll
;       for (int ni = 0; ni < 4; ++ni)
; #pragma unroll
;         for (int j = 0; j < 4; ++j) Cw[(g * 4 + j) * 68 + ni * 16 + r] = acc[mi][ni][j];
	s_waitcnt vmcnt(7)
	ds_write_b128 v198, v[18:21]
	s_waitcnt vmcnt(5)
	ds_write_b128 v198, v[86:89] offset:8192
	s_waitcnt vmcnt(4)
	ds_write_b128 v198, v[90:93] offset:16384
	s_waitcnt vmcnt(3)
	ds_write_b128 v198, v[94:97] offset:24576
	ds_write_b128 v198, v[98:101] offset:32768
	s_waitcnt vmcnt(2)
	ds_write_b128 v198, v[102:105] offset:40960
	s_waitcnt vmcnt(1)
	ds_write_b128 v198, v[106:109] offset:49152
	s_waitcnt vmcnt(0)
	ds_write_b128 v198, v[110:113] offset:57344
	s_movk_i32 s2, 0x1100
	v_lshrrev_b32_e32 v0, 6, v14
	v_mul_lo_u32 v19, v0, s2
	s_min_i32 s2, s60, 0x8000
	s_lshr_b32 s2, s2, 11
	s_mul_i32 s46, s50, 17
	v_and_b32_e32 v0, 0xc0, v14
	s_add_i32 s2, s2, s46
	v_readlane_b32 s64, v255, 28
	v_or_b32_e32 v0, s61, v0
	s_mul_hi_i32 s47, s2, 0x3000
	s_mulk_i32 s2, 0x3000
	v_readlane_b32 s66, v255, 30
	v_readlane_b32 s67, v255, 31
	s_add_u32 s46, s66, s2
	v_lshlrev_b64 v[10:11], 2, v[0:1]
	v_mov_b32_e32 v0, 0x8000
	s_addc_u32 s47, s67, s47
	v_sub_co_u32_e32 v0, vcc, s60, v0
	v_lshl_add_u64 v[12:13], s[46:47], 0, v[10:11]
	s_and_b64 s[46:47], vcc, exec
	v_readfirstlane_b32 s2, v0
	s_cselect_b32 s2, s60, s2
	s_cselect_b32 s48, 0, 16
	s_and_b64 s[46:47], s[0:1], exec
	s_cselect_b32 s46, s48, 0x88
	s_cselect_b32 s2, s2, s60
	s_add_u32 s46, s96, s46
	s_addc_u32 s47, s97, 0
	s_load_dwordx2 s[46:47], s[46:47], 0x0
	v_ashrrev_i32_e32 v0, 1, v14
	v_and_b32_e32 v18, 15, v14
	v_bfe_u32 v88, v14, 4, 2
	s_lshl_b64 s[48:49], s[2:3], 12
	v_and_b32_e32 v14, 0xffffff80, v0
	s_waitcnt lgkmcnt(0)
	s_add_u32 s46, s46, s48
	v_ashrrev_i32_e32 v15, 31, v14
	s_addc_u32 s47, s47, s49
	v_lshlrev_b64 v[16:17], 12, v[14:15]
	v_lshl_add_u64 v[16:17], s[46:47], 0, v[16:17]
	v_add_u32_e32 v14, s60, v14
	v_lshl_add_u64 v[16:17], v[16:17], 0, v[10:11]
	v_ashrrev_i32_e32 v15, 31, v14
	v_lshlrev_b32_e32 v0, 4, v18
	v_lshlrev_b64 v[14:15], 12, v[14:15]
	v_lshlrev_b32_e32 v20, 2, v18
	v_lshl_add_u64 v[16:17], v[16:17], 0, v[0:1]
	v_lshlrev_b32_e32 v86, 12, v88
	v_mov_b32_e32 v87, v1
	v_lshl_add_u64 v[14:15], s[18:19], 0, v[14:15]
	v_lshl_add_u64 v[162:163], v[16:17], 0, v[86:87]
	v_add3_u32 v16, s78, v19, v20
	s_movk_i32 s2, 0x440
	v_lshl_add_u64 v[12:13], v[12:13], 0, v[0:1]
	v_lshl_add_u64 v[10:11], v[14:15], 0, v[10:11]
	v_mad_u32_u24 v165, v88, s2, v16
	s_movk_i32 s2, 0x2000
	v_lshl_add_u64 v[14:15], v[10:11], 0, v[0:1]
	v_add_co_u32_e32 v10, vcc, s2, v12
	ds_write2_b32 v165, v146, v154 offset1:16
	ds_write2_b32 v165, v147, v155 offset0:68 offset1:84
	ds_write2_b32 v165, v148, v156 offset0:136 offset1:152
	ds_write2_b32 v165, v149, v157 offset0:204 offset1:220
	ds_write2_b32 v165, v150, v158 offset0:32 offset1:48
	ds_write2_b32 v165, v151, v159 offset0:100 offset1:116
	ds_write2_b32 v165, v152, v160 offset0:168 offset1:184
	ds_write2_b32 v165, v153, v161 offset0:236 offset1:252
	v_addc_co_u32_e32 v11, vcc, 0, v13, vcc
	v_mad_u32_u24 v17, v18, 12, v16
	global_load_dwordx4 v[18:21], v[10:11], off
	s_nop 0
	global_load_dwordx4 v[10:13], v[162:163], off
	v_or_b32_e32 v0, 4, v88
	v_add_co_u32_e32 v16, vcc, s94, v162
	v_mad_u32_u24 v164, v88, s79, v17
	v_mad_u32_u24 v158, v0, s79, v17
	v_addc_co_u32_e32 v17, vcc, 0, v163, vcc
	global_load_dwordx4 v[102:105], v[16:17], off
	v_add_co_u32_e32 v16, vcc, s21, v162
	v_lshlrev_b32_e32 v0, 12, v0
	s_nop 0
	v_addc_co_u32_e32 v17, vcc, 0, v163, vcc
	global_load_dwordx4 v[94:97], v[16:17], off
	v_lshl_add_u64 v[156:157], v[14:15], 0, v[0:1]
	v_or_b32_e32 v0, 0x8000, v86
	v_lshl_add_u64 v[154:155], v[14:15], 0, v[0:1]
	v_or_b32_e32 v0, 0xc000, v86
	s_mov_b32 s2, 0xc000
	v_lshl_add_u64 v[152:153], v[14:15], 0, v[86:87]
	v_lshl_add_u64 v[150:151], v[14:15], 0, v[0:1]
	v_add_co_u32_e32 v14, vcc, s2, v162
	s_mov_b32 s2, 0x14000
	s_nop 0
	v_addc_co_u32_e32 v15, vcc, 0, v163, vcc
	global_load_dwordx4 v[86:89], v[14:15], off
	v_add_co_u32_e32 v14, vcc, s85, v162
	s_mov_b32 s46, 0x30000
	s_nop 0
	v_addc_co_u32_e32 v15, vcc, 0, v163, vcc
	global_load_dwordx4 v[146:149], v[14:15], off
	v_add_co_u32_e32 v14, vcc, s2, v162
	s_mov_b32 s2, 0x18000
	s_nop 0
	v_addc_co_u32_e32 v15, vcc, 0, v163, vcc
	global_load_dwordx4 v[106:109], v[14:15], off
	v_add_co_u32_e32 v14, vcc, s2, v162
	s_mov_b32 s2, 0x1c000
	s_nop 0
	v_addc_co_u32_e32 v15, vcc, 0, v163, vcc
	global_load_dwordx4 v[98:101], v[14:15], off
	v_add_co_u32_e32 v14, vcc, s2, v162
	s_mov_b32 s2, 0x24000
	s_nop 0
	v_addc_co_u32_e32 v15, vcc, 0, v163, vcc
	global_load_dwordx4 v[90:93], v[14:15], off
	ds_read_b128 v[14:17], v164
	s_mov_b32 s60, s58
	s_mov_b32 s61, s59
	s_mov_b64 s[48:49], s[42:43]
	v_readlane_b32 s65, v255, 29
	v_readlane_b32 s68, v255, 32
	v_readlane_b32 s69, v255, 33
	v_readlane_b32 s70, v255, 34
	v_readlane_b32 s71, v255, 35
	s_waitcnt vmcnt(8) lgkmcnt(0)
	v_pk_mul_f32 v[14:15], v[18:19], v[14:15]
	s_waitcnt vmcnt(7)
	v_pk_fma_f32 v[10:11], v[10:11], s[34:35], v[14:15] op_sel_hi:[1,0,1]
	v_pk_mul_f32 v[14:15], v[20:21], v[16:17]
	s_nop 0
	v_pk_fma_f32 v[12:13], v[12:13], s[34:35], v[14:15] op_sel_hi:[1,0,1]
	global_store_dwordx4 v[152:153], v[10:13], off
	ds_read_b128 v[10:13], v158
	s_waitcnt lgkmcnt(0)
	v_pk_mul_f32 v[10:11], v[18:19], v[10:11]
	v_pk_mul_f32 v[12:13], v[20:21], v[12:13]
	s_waitcnt vmcnt(7)
	v_pk_fma_f32 v[10:11], v[102:103], s[34:35], v[10:11] op_sel_hi:[1,0,1]
	v_pk_fma_f32 v[12:13], v[104:105], s[34:35], v[12:13] op_sel_hi:[1,0,1]
	global_store_dwordx4 v[156:157], v[10:13], off
	ds_read_b128 v[10:13], v158 offset:1088
	s_waitcnt lgkmcnt(0)
	v_pk_mul_f32 v[10:11], v[18:19], v[10:11]
	v_pk_mul_f32 v[12:13], v[20:21], v[12:13]
	s_waitcnt vmcnt(7)
; template <int EPI>
; DI void gemm_phase(const P& p, int l, const u16* __restrict__ A, const u16* __restrict__ Bt, int mpx, char* lds) {
;     ...
;     for (int mi = 0; mi < 8; ++mi) {
;       float4 xv[4];
; #pragma unroll
;       for (int i = 0; i < 4; ++i) xv[i] = xn[i];
;       if (mi < 7) {
; #pragma unroll
;         for (int i = 0; i < 4; ++i) xn[i] = *(const float4*)(xr + (size_t)((mi + 1) * 16 + rr0 + 4 * i) * 1024 + c4);
;       }
; #pragma unroll
;       for (int ni = 0; ni < 4; ++ni)
; #pragma unroll
;         for (int j = 0; j < 4; ++j) Cw[(g * 4 + j) * 68 + ni * 16 + r] = acc[mi][ni][j];
;       __builtin_amdgcn_fence(__ATOMIC_RELEASE, "wavefront");
; #pragma unroll
;       for (int i = 0; i < 4; ++i) {
;         const int row = rr0 + 4 * i;
;         const float4 a = *(const float4*)&Cw[row * 68 + c4];
;         float4 z;
;         z.x = alpha * xv[i].x + gt.x * a.x;
;         z.y = alpha * xv[i].y + gt.y * a.y;
;         z.z = alpha * xv[i].z + gt.z * a.z;
;         z.w = alpha * xv[i].w + gt.w * a.w;
;         *(float4*)(Z + (size_t)(mi * 16 + row) * 1024 + c4) = z;
;       }
;       __builtin_amdgcn_fence(__ATOMIC_RELEASE, "wavefront");
	v_pk_fma_f32 v[10:11], v[94:95], s[34:35], v[10:11] op_sel_hi:[1,0,1]
	v_pk_fma_f32 v[12:13], v[96:97], s[34:35], v[12:13] op_sel_hi:[1,0,1]
	global_store_dwordx4 v[154:155], v[10:13], off
	ds_read_b128 v[10:13], v158 offset:2176
	s_waitcnt lgkmcnt(0)
	v_pk_mul_f32 v[10:11], v[18:19], v[10:11]
	v_pk_mul_f32 v[12:13], v[20:21], v[12:13]
	s_waitcnt vmcnt(7)
	v_pk_fma_f32 v[10:11], v[86:87], s[34:35], v[10:11] op_sel_hi:[1,0,1]
	v_pk_fma_f32 v[12:13], v[88:89], s[34:35], v[12:13] op_sel_hi:[1,0,1]
	global_store_dwordx4 v[150:151], v[10:13], off
	ds_write2_b32 v165, v138, v142 offset1:16
	ds_write2_b32 v165, v139, v143 offset0:68 offset1:84
	ds_write2_b32 v165, v140, v144 offset0:136 offset1:152
	ds_write2_b32 v165, v141, v145 offset0:204 offset1:220
	ds_write2_b32 v165, v130, v134 offset0:32 offset1:48
	ds_write2_b32 v165, v131, v135 offset0:100 offset1:116
	ds_write2_b32 v165, v132, v136 offset0:168 offset1:184
	ds_write2_b32 v165, v133, v137 offset0:236 offset1:252
	v_add_co_u32_e32 v10, vcc, s33, v162
	s_nop 1
	v_addc_co_u32_e32 v11, vcc, 0, v163, vcc
	global_load_dwordx4 v[110:113], v[10:11], off
	v_add_co_u32_e32 v10, vcc, s2, v162
	s_mov_b32 s2, 0x28000
	s_nop 0
	v_addc_co_u32_e32 v11, vcc, 0, v163, vcc
	global_load_dwordx4 v[102:105], v[10:11], off
	v_add_co_u32_e32 v10, vcc, s2, v162
	s_mov_b32 s2, 0x2c000
	s_nop 0
	v_addc_co_u32_e32 v11, vcc, 0, v163, vcc
	global_load_dwordx4 v[94:97], v[10:11], off
	v_add_co_u32_e32 v10, vcc, s2, v162
	s_mov_b32 s2, 0x34000
	s_nop 0
	v_addc_co_u32_e32 v11, vcc, 0, v163, vcc
	global_load_dwordx4 v[86:89], v[10:11], off
	ds_read_b128 v[10:13], v164
	v_add_co_u32_e32 v14, vcc, s85, v152
	s_waitcnt lgkmcnt(0)
	v_pk_mul_f32 v[10:11], v[18:19], v[10:11]
	v_pk_mul_f32 v[12:13], v[20:21], v[12:13]
	s_waitcnt vmcnt(11)
	v_pk_fma_f32 v[10:11], v[146:147], s[34:35], v[10:11] op_sel_hi:[1,0,1]
	v_pk_fma_f32 v[12:13], v[148:149], s[34:35], v[12:13] op_sel_hi:[1,0,1]
	v_addc_co_u32_e32 v15, vcc, 0, v153, vcc
	global_store_dwordx4 v[14:15], v[10:13], off
	ds_read_b128 v[10:13], v158
	v_add_co_u32_e32 v14, vcc, s85, v156
	s_waitcnt lgkmcnt(0)
	v_pk_mul_f32 v[10:11], v[18:19], v[10:11]
	v_pk_mul_f32 v[12:13], v[20:21], v[12:13]
	s_waitcnt vmcnt(11)
	v_pk_fma_f32 v[10:11], v[106:107], s[34:35], v[10:11] op_sel_hi:[1,0,1]
	v_pk_fma_f32 v[12:13], v[108:109], s[34:35], v[12:13] op_sel_hi:[1,0,1]
	v_addc_co_u32_e32 v15, vcc, 0, v157, vcc
	global_store_dwordx4 v[14:15], v[10:13], off
	ds_read_b128 v[10:13], v158 offset:1088
	v_add_co_u32_e32 v14, vcc, s85, v154
	s_waitcnt lgkmcnt(0)
	v_pk_mul_f32 v[10:11], v[18:19], v[10:11]
	v_pk_mul_f32 v[12:13], v[20:21], v[12:13]
	s_waitcnt vmcnt(11)
	v_pk_fma_f32 v[10:11], v[98:99], s[34:35], v[10:11] op_sel_hi:[1,0,1]
	v_pk_fma_f32 v[12:13], v[100:101], s[34:35], v[12:13] op_sel_hi:[1,0,1]
	v_addc_co_u32_e32 v15, vcc, 0, v155, vcc
	global_store_dwordx4 v[14:15], v[10:13], off
	ds_read_b128 v[10:13], v158 offset:2176
	v_add_co_u32_e32 v14, vcc, s85, v150
	s_waitcnt lgkmcnt(0)
	v_pk_mul_f32 v[10:11], v[18:19], v[10:11]
	v_pk_mul_f32 v[12:13], v[20:21], v[12:13]
	s_waitcnt vmcnt(11)
	v_pk_fma_f32 v[10:11], v[90:91], s[34:35], v[10:11] op_sel_hi:[1,0,1]
	v_pk_fma_f32 v[12:13], v[92:93], s[34:35], v[12:13] op_sel_hi:[1,0,1]
	v_addc_co_u32_e32 v15, vcc, 0, v151, vcc
	global_store_dwordx4 v[14:15], v[10:13], off
	ds_write2_b32 v165, v122, v126 offset1:16
	ds_write2_b32 v165, v123, v127 offset0:68 offset1:84
	ds_write2_b32 v165, v124, v128 offset0:136 offset1:152
	ds_write2_b32 v165, v125, v129 offset0:204 offset1:220
	ds_write2_b32 v165, v114, v118 offset0:32 offset1:48
	ds_write2_b32 v165, v115, v119 offset0:100 offset1:116
	ds_write2_b32 v165, v116, v120 offset0:168 offset1:184
	ds_write2_b32 v165, v117, v121 offset0:236 offset1:252
	v_add_co_u32_e32 v10, vcc, s46, v162
	s_nop 1
	v_addc_co_u32_e32 v11, vcc, 0, v163, vcc
	global_load_dwordx4 v[114:117], v[10:11], off
	v_add_co_u32_e32 v10, vcc, s2, v162
	s_mov_b32 s2, 0x38000
	s_nop 0
	v_addc_co_u32_e32 v11, vcc, 0, v163, vcc
	global_load_dwordx4 v[106:109], v[10:11], off
	v_add_co_u32_e32 v10, vcc, s2, v162
	s_mov_b32 s2, 0x3c000
	s_nop 0
	v_addc_co_u32_e32 v11, vcc, 0, v163, vcc
	global_load_dwordx4 v[98:101], v[10:11], off
	v_add_co_u32_e32 v10, vcc, s2, v162
	s_mov_b32 s2, 0x44000
	s_nop 0
	v_addc_co_u32_e32 v11, vcc, 0, v163, vcc
	global_load_dwordx4 v[90:93], v[10:11], off
	ds_read_b128 v[10:13], v164
	v_add_co_u32_e32 v14, vcc, s33, v152
	s_waitcnt lgkmcnt(0)
	v_pk_mul_f32 v[10:11], v[18:19], v[10:11]
	v_pk_mul_f32 v[12:13], v[20:21], v[12:13]
	s_waitcnt vmcnt(11)
	v_pk_fma_f32 v[10:11], v[110:111], s[34:35], v[10:11] op_sel_hi:[1,0,1]
	v_pk_fma_f32 v[12:13], v[112:113], s[34:35], v[12:13] op_sel_hi:[1,0,1]
	v_addc_co_u32_e32 v15, vcc, 0, v153, vcc
	global_store_dwordx4 v[14:15], v[10:13], off
	ds_read_b128 v[10:13], v158
	v_add_co_u32_e32 v14, vcc, s33, v156
	s_waitcnt lgkmcnt(0)
	v_pk_mul_f32 v[10:11], v[18:19], v[10:11]
	v_pk_mul_f32 v[12:13], v[20:21], v[12:13]
	s_waitcnt vmcnt(11)
	v_pk_fma_f32 v[10:11], v[102:103], s[34:35], v[10:11] op_sel_hi:[1,0,1]
	v_pk_fma_f32 v[12:13], v[104:105], s[34:35], v[12:13] op_sel_hi:[1,0,1]
	v_addc_co_u32_e32 v15, vcc, 0, v157, vcc
	global_store_dwordx4 v[14:15], v[10:13], off
	ds_read_b128 v[10:13], v158 offset:1088
	v_add_co_u32_e32 v14, vcc, s33, v154
	s_waitcnt lgkmcnt(0)
	v_pk_mul_f32 v[10:11], v[18:19], v[10:11]
	v_pk_mul_f32 v[12:13], v[20:21], v[12:13]
	s_waitcnt vmcnt(11)
	v_pk_fma_f32 v[10:11], v[94:95], s[34:35], v[10:11] op_sel_hi:[1,0,1]
	v_pk_fma_f32 v[12:13], v[96:97], s[34:35], v[12:13] op_sel_hi:[1,0,1]
	v_addc_co_u32_e32 v15, vcc, 0, v155, vcc
	global_store_dwordx4 v[14:15], v[10:13], off
	ds_read_b128 v[10:13], v158 offset:2176
	v_add_co_u32_e32 v14, vcc, s33, v150
	s_waitcnt lgkmcnt(0)
; template <int EPI>
; DI void gemm_phase(const P& p, int l, const u16* __restrict__ A, const u16* __restrict__ Bt, int mpx, char* lds) {
;     ...
;     for (int mi = 0; mi < 8; ++mi) {
;       float4 xv[4];
; #pragma unroll
;       for (int i = 0; i < 4; ++i) xv[i] = xn[i];
;       if (mi < 7) {
; #pragma unroll
;         for (int i = 0; i < 4; ++i) xn[i] = *(const float4*)(xr + (size_t)((mi + 1) * 16 + rr0 + 4 * i) * 1024 + c4);
;       }
; #pragma unroll
;       for (int ni = 0; ni < 4; ++ni)
; #pragma unroll
;         for (int j = 0; j < 4; ++j) Cw[(g * 4 + j) * 68 + ni * 16 + r] = acc[mi][ni][j];
;       __builtin_amdgcn_fence(__ATOMIC_RELEASE, "wavefront");
; #pragma unroll
;       for (int i = 0; i < 4; ++i) {
;         const int row = rr0 + 4 * i;
;         const float4 a = *(const float4*)&Cw[row * 68 + c4];
;         float4 z;
;         z.x = alpha * xv[i].x + gt.x * a.x;
;         z.y = alpha * xv[i].y + gt.y * a.y;
;         z.z = alpha * xv[i].z + gt.z * a.z;
;         z.w = alpha * xv[i].w + gt.w * a.w;
;         *(float4*)(Z + (size_t)(mi * 16 + row) * 1024 + c4) = z;
;       }
;       __builtin_amdgcn_fence(__ATOMIC_RELEASE, "wavefront");
	v_pk_mul_f32 v[10:11], v[18:19], v[10:11]
	v_pk_mul_f32 v[12:13], v[20:21], v[12:13]
	s_waitcnt vmcnt(11)
	v_pk_fma_f32 v[10:11], v[86:87], s[34:35], v[10:11] op_sel_hi:[1,0,1]
	v_pk_fma_f32 v[12:13], v[88:89], s[34:35], v[12:13] op_sel_hi:[1,0,1]
	v_addc_co_u32_e32 v15, vcc, 0, v151, vcc
	global_store_dwordx4 v[14:15], v[10:13], off
	ds_write2_b32 v165, v78, v82 offset1:16
	ds_write2_b32 v165, v79, v83 offset0:68 offset1:84
	ds_write2_b32 v165, v80, v84 offset0:136 offset1:152
	ds_write2_b32 v165, v81, v85 offset0:204 offset1:220
	ds_write2_b32 v165, v70, v74 offset0:32 offset1:48
	ds_write2_b32 v165, v71, v75 offset0:100 offset1:116
	ds_write2_b32 v165, v72, v76 offset0:168 offset1:184
	ds_write2_b32 v165, v73, v77 offset0:236 offset1:252
	v_add_co_u32_e32 v10, vcc, s35, v162
	s_nop 1
	v_addc_co_u32_e32 v11, vcc, 0, v163, vcc
	global_load_dwordx4 v[82:85], v[10:11], off
	v_add_co_u32_e32 v10, vcc, s2, v162
	s_mov_b32 s2, 0x48000
	s_nop 0
	v_addc_co_u32_e32 v11, vcc, 0, v163, vcc
	global_load_dwordx4 v[78:81], v[10:11], off
	v_add_co_u32_e32 v10, vcc, s2, v162
	s_mov_b32 s2, 0x4c000
	s_nop 0
	v_addc_co_u32_e32 v11, vcc, 0, v163, vcc
	global_load_dwordx4 v[74:77], v[10:11], off
	v_add_co_u32_e32 v10, vcc, s2, v162
	s_mov_b32 s2, 0x54000
	s_nop 0
	v_addc_co_u32_e32 v11, vcc, 0, v163, vcc
	global_load_dwordx4 v[70:73], v[10:11], off
	ds_read_b128 v[10:13], v164
	v_add_co_u32_e32 v14, vcc, s46, v152
	s_waitcnt lgkmcnt(0)
	v_pk_mul_f32 v[10:11], v[18:19], v[10:11]
	v_pk_mul_f32 v[12:13], v[20:21], v[12:13]
	s_waitcnt vmcnt(11)
	v_pk_fma_f32 v[10:11], v[114:115], s[34:35], v[10:11] op_sel_hi:[1,0,1]
	v_pk_fma_f32 v[12:13], v[116:117], s[34:35], v[12:13] op_sel_hi:[1,0,1]
	v_addc_co_u32_e32 v15, vcc, 0, v153, vcc
	global_store_dwordx4 v[14:15], v[10:13], off
	ds_read_b128 v[10:13], v158
	v_add_co_u32_e32 v14, vcc, s46, v156
	s_waitcnt lgkmcnt(0)
	v_pk_mul_f32 v[10:11], v[18:19], v[10:11]
	v_pk_mul_f32 v[12:13], v[20:21], v[12:13]
	s_waitcnt vmcnt(11)
	v_pk_fma_f32 v[10:11], v[106:107], s[34:35], v[10:11] op_sel_hi:[1,0,1]
	v_pk_fma_f32 v[12:13], v[108:109], s[34:35], v[12:13] op_sel_hi:[1,0,1]
	v_addc_co_u32_e32 v15, vcc, 0, v157, vcc
	global_store_dwordx4 v[14:15], v[10:13], off
	ds_read_b128 v[10:13], v158 offset:1088
	v_add_co_u32_e32 v14, vcc, s46, v154
	s_waitcnt lgkmcnt(0)
	v_pk_mul_f32 v[10:11], v[18:19], v[10:11]
	v_pk_mul_f32 v[12:13], v[20:21], v[12:13]
	s_waitcnt vmcnt(11)
	v_pk_fma_f32 v[10:11], v[98:99], s[34:35], v[10:11] op_sel_hi:[1,0,1]
	v_pk_fma_f32 v[12:13], v[100:101], s[34:35], v[12:13] op_sel_hi:[1,0,1]
	v_addc_co_u32_e32 v15, vcc, 0, v155, vcc
	global_store_dwordx4 v[14:15], v[10:13], off
	ds_read_b128 v[10:13], v158 offset:2176
	v_add_co_u32_e32 v14, vcc, s46, v150
	s_mov_b32 s46, 0x50000
	s_nop 0
	v_addc_co_u32_e32 v15, vcc, 0, v151, vcc
	s_waitcnt lgkmcnt(0)
	v_pk_mul_f32 v[10:11], v[18:19], v[10:11]
	v_pk_mul_f32 v[12:13], v[20:21], v[12:13]
	s_waitcnt vmcnt(11)
	v_pk_fma_f32 v[10:11], v[90:91], s[34:35], v[10:11] op_sel_hi:[1,0,1]
	v_pk_fma_f32 v[12:13], v[92:93], s[34:35], v[12:13] op_sel_hi:[1,0,1]
	global_store_dwordx4 v[14:15], v[10:13], off
	ds_write2_b32 v165, v62, v66 offset1:16
	ds_write2_b32 v165, v63, v67 offset0:68 offset1:84
	ds_write2_b32 v165, v64, v68 offset0:136 offset1:152
	ds_write2_b32 v165, v65, v69 offset0:204 offset1:220
	ds_write2_b32 v165, v54, v58 offset0:32 offset1:48
	ds_write2_b32 v165, v55, v59 offset0:100 offset1:116
	ds_write2_b32 v165, v56, v60 offset0:168 offset1:184
	ds_write2_b32 v165, v57, v61 offset0:236 offset1:252
	v_add_co_u32_e32 v10, vcc, s46, v162
	s_nop 1
	v_addc_co_u32_e32 v11, vcc, 0, v163, vcc
	global_load_dwordx4 v[66:69], v[10:11], off
	v_add_co_u32_e32 v10, vcc, s2, v162
	s_mov_b32 s2, 0x58000
	s_nop 0
	v_addc_co_u32_e32 v11, vcc, 0, v163, vcc
	global_load_dwordx4 v[62:65], v[10:11], off
	v_add_co_u32_e32 v10, vcc, s2, v162
	s_mov_b32 s2, 0x5c000
	s_nop 0
	v_addc_co_u32_e32 v11, vcc, 0, v163, vcc
	global_load_dwordx4 v[58:61], v[10:11], off
	v_add_co_u32_e32 v10, vcc, s2, v162
	s_mov_b32 s2, 0x64000
	s_nop 0
	v_addc_co_u32_e32 v11, vcc, 0, v163, vcc
	global_load_dwordx4 v[54:57], v[10:11], off
	ds_read_b128 v[10:13], v164
	v_add_co_u32_e32 v14, vcc, s35, v152
	s_waitcnt lgkmcnt(0)
	v_pk_mul_f32 v[10:11], v[18:19], v[10:11]
	v_pk_mul_f32 v[12:13], v[20:21], v[12:13]
	s_waitcnt vmcnt(11)
	v_pk_fma_f32 v[10:11], v[82:83], s[34:35], v[10:11] op_sel_hi:[1,0,1]
	v_pk_fma_f32 v[12:13], v[84:85], s[34:35], v[12:13] op_sel_hi:[1,0,1]
	v_addc_co_u32_e32 v15, vcc, 0, v153, vcc
	global_store_dwordx4 v[14:15], v[10:13], off
	ds_read_b128 v[10:13], v158
	v_add_co_u32_e32 v14, vcc, s35, v156
	s_waitcnt lgkmcnt(0)
	v_pk_mul_f32 v[10:11], v[18:19], v[10:11]
	v_pk_mul_f32 v[12:13], v[20:21], v[12:13]
	s_waitcnt vmcnt(11)
	v_pk_fma_f32 v[10:11], v[78:79], s[34:35], v[10:11] op_sel_hi:[1,0,1]
	v_pk_fma_f32 v[12:13], v[80:81], s[34:35], v[12:13] op_sel_hi:[1,0,1]
	v_addc_co_u32_e32 v15, vcc, 0, v157, vcc
	global_store_dwordx4 v[14:15], v[10:13], off
	ds_read_b128 v[10:13], v158 offset:1088
	v_add_co_u32_e32 v14, vcc, s35, v154
	s_waitcnt lgkmcnt(0)
	v_pk_mul_f32 v[10:11], v[18:19], v[10:11]
	v_pk_mul_f32 v[12:13], v[20:21], v[12:13]
	s_waitcnt vmcnt(11)
	v_pk_fma_f32 v[10:11], v[74:75], s[34:35], v[10:11] op_sel_hi:[1,0,1]
	v_pk_fma_f32 v[12:13], v[76:77], s[34:35], v[12:13] op_sel_hi:[1,0,1]
	v_addc_co_u32_e32 v15, vcc, 0, v155, vcc
	global_store_dwordx4 v[14:15], v[10:13], off
	ds_read_b128 v[10:13], v158 offset:2176
	v_add_co_u32_e32 v14, vcc, s35, v150
	s_waitcnt lgkmcnt(0)
	v_pk_mul_f32 v[10:11], v[18:19], v[10:11]
	v_pk_mul_f32 v[12:13], v[20:21], v[12:13]
	s_waitcnt vmcnt(11)
; template <int EPI>
; DI void gemm_phase(const P& p, int l, const u16* __restrict__ A, const u16* __restrict__ Bt, int mpx, char* lds) {
;     ...
;     for (int mi = 0; mi < 8; ++mi) {
;       float4 xv[4];
; #pragma unroll
;       for (int i = 0; i < 4; ++i) xv[i] = xn[i];
;       if (mi < 7) {
; #pragma unroll
;         for (int i = 0; i < 4; ++i) xn[i] = *(const float4*)(xr + (size_t)((mi + 1) * 16 + rr0 + 4 * i) * 1024 + c4);
;       }
; #pragma unroll
;       for (int ni = 0; ni < 4; ++ni)
; #pragma unroll
;         for (int j = 0; j < 4; ++j) Cw[(g * 4 + j) * 68 + ni * 16 + r] = acc[mi][ni][j];
;       __builtin_amdgcn_fence(__ATOMIC_RELEASE, "wavefront");
; #pragma unroll
;       for (int i = 0; i < 4; ++i) {
;         const int row = rr0 + 4 * i;
;         const float4 a = *(const float4*)&Cw[row * 68 + c4];
;         float4 z;
;         z.x = alpha * xv[i].x + gt.x * a.x;
;         z.y = alpha * xv[i].y + gt.y * a.y;
;         z.z = alpha * xv[i].z + gt.z * a.z;
;         z.w = alpha * xv[i].w + gt.w * a.w;
;         *(float4*)(Z + (size_t)(mi * 16 + row) * 1024 + c4) = z;
;       }
;       __builtin_amdgcn_fence(__ATOMIC_RELEASE, "wavefront");
	v_pk_fma_f32 v[10:11], v[70:71], s[34:35], v[10:11] op_sel_hi:[1,0,1]
	v_pk_fma_f32 v[12:13], v[72:73], s[34:35], v[12:13] op_sel_hi:[1,0,1]
	v_addc_co_u32_e32 v15, vcc, 0, v151, vcc
	global_store_dwordx4 v[14:15], v[10:13], off
	ds_write2_b32 v165, v46, v50 offset1:16
	ds_write2_b32 v165, v47, v51 offset0:68 offset1:84
	ds_write2_b32 v165, v48, v52 offset0:136 offset1:152
	ds_write2_b32 v165, v49, v53 offset0:204 offset1:220
	ds_write2_b32 v165, v38, v42 offset0:32 offset1:48
	ds_write2_b32 v165, v39, v43 offset0:100 offset1:116
	ds_write2_b32 v165, v40, v44 offset0:168 offset1:184
	ds_write2_b32 v165, v41, v45 offset0:236 offset1:252
	v_add_co_u32_e32 v10, vcc, s39, v162
	s_nop 1
	v_addc_co_u32_e32 v11, vcc, 0, v163, vcc
	global_load_dwordx4 v[50:53], v[10:11], off
	v_add_co_u32_e32 v10, vcc, s2, v162
	s_mov_b32 s2, 0x68000
	s_nop 0
	v_addc_co_u32_e32 v11, vcc, 0, v163, vcc
	global_load_dwordx4 v[46:49], v[10:11], off
	v_add_co_u32_e32 v10, vcc, s2, v162
	s_mov_b32 s2, 0x6c000
	s_nop 0
	v_addc_co_u32_e32 v11, vcc, 0, v163, vcc
	global_load_dwordx4 v[42:45], v[10:11], off
	v_add_co_u32_e32 v10, vcc, s2, v162
	s_mov_b32 s2, 0x74000
	s_nop 0
	v_addc_co_u32_e32 v11, vcc, 0, v163, vcc
	global_load_dwordx4 v[38:41], v[10:11], off
	ds_read_b128 v[10:13], v164
	v_add_co_u32_e32 v14, vcc, s46, v152
	s_waitcnt lgkmcnt(0)
	v_pk_mul_f32 v[10:11], v[18:19], v[10:11]
	v_pk_mul_f32 v[12:13], v[20:21], v[12:13]
	s_waitcnt vmcnt(11)
	v_pk_fma_f32 v[10:11], v[66:67], s[34:35], v[10:11] op_sel_hi:[1,0,1]
	v_pk_fma_f32 v[12:13], v[68:69], s[34:35], v[12:13] op_sel_hi:[1,0,1]
	v_addc_co_u32_e32 v15, vcc, 0, v153, vcc
	global_store_dwordx4 v[14:15], v[10:13], off
	ds_read_b128 v[10:13], v158
	v_add_co_u32_e32 v14, vcc, s46, v156
	s_waitcnt lgkmcnt(0)
	v_pk_mul_f32 v[10:11], v[18:19], v[10:11]
	v_pk_mul_f32 v[12:13], v[20:21], v[12:13]
	s_waitcnt vmcnt(11)
	v_pk_fma_f32 v[10:11], v[62:63], s[34:35], v[10:11] op_sel_hi:[1,0,1]
	v_pk_fma_f32 v[12:13], v[64:65], s[34:35], v[12:13] op_sel_hi:[1,0,1]
	v_addc_co_u32_e32 v15, vcc, 0, v157, vcc
	global_store_dwordx4 v[14:15], v[10:13], off
	ds_read_b128 v[10:13], v158 offset:1088
	v_add_co_u32_e32 v14, vcc, s46, v154
	s_waitcnt lgkmcnt(0)
	v_pk_mul_f32 v[10:11], v[18:19], v[10:11]
	v_pk_mul_f32 v[12:13], v[20:21], v[12:13]
	s_waitcnt vmcnt(11)
	v_pk_fma_f32 v[10:11], v[58:59], s[34:35], v[10:11] op_sel_hi:[1,0,1]
	v_pk_fma_f32 v[12:13], v[60:61], s[34:35], v[12:13] op_sel_hi:[1,0,1]
	v_addc_co_u32_e32 v15, vcc, 0, v155, vcc
	global_store_dwordx4 v[14:15], v[10:13], off
	ds_read_b128 v[10:13], v158 offset:2176
	v_add_co_u32_e32 v14, vcc, s46, v150
	s_mov_b32 s46, 0x70000
	s_nop 0
	v_addc_co_u32_e32 v15, vcc, 0, v151, vcc
	s_waitcnt lgkmcnt(0)
	v_pk_mul_f32 v[10:11], v[18:19], v[10:11]
	v_pk_mul_f32 v[12:13], v[20:21], v[12:13]
	s_waitcnt vmcnt(11)
	v_pk_fma_f32 v[10:11], v[54:55], s[34:35], v[10:11] op_sel_hi:[1,0,1]
	v_pk_fma_f32 v[12:13], v[56:57], s[34:35], v[12:13] op_sel_hi:[1,0,1]
	global_store_dwordx4 v[14:15], v[10:13], off
	ds_write2_b32 v165, v30, v34 offset1:16
	ds_write2_b32 v165, v31, v35 offset0:68 offset1:84
	ds_write2_b32 v165, v32, v36 offset0:136 offset1:152
	ds_write2_b32 v165, v33, v37 offset0:204 offset1:220
	ds_write2_b32 v165, v22, v26 offset0:32 offset1:48
	ds_write2_b32 v165, v23, v27 offset0:100 offset1:116
	ds_write2_b32 v165, v24, v28 offset0:168 offset1:184
	ds_write2_b32 v165, v25, v29 offset0:236 offset1:252
	v_add_co_u32_e32 v10, vcc, s46, v162
	s_nop 1
	v_addc_co_u32_e32 v11, vcc, 0, v163, vcc
	global_load_dwordx4 v[10:13], v[10:11], off
	v_add_co_u32_e32 v14, vcc, s2, v162
	s_mov_b32 s2, 0x78000
	s_nop 0
	v_addc_co_u32_e32 v15, vcc, 0, v163, vcc
	global_load_dwordx4 v[30:33], v[14:15], off
	v_add_co_u32_e32 v14, vcc, s2, v162
	s_mov_b32 s2, 0x7c000
	s_nop 0
	v_addc_co_u32_e32 v15, vcc, 0, v163, vcc
	global_load_dwordx4 v[26:29], v[14:15], off
	v_add_co_u32_e32 v14, vcc, s2, v162
	s_nop 1
	v_addc_co_u32_e32 v15, vcc, 0, v163, vcc
	global_load_dwordx4 v[22:25], v[14:15], off
	ds_read_b128 v[14:17], v164
	v_add_co_u32_e32 v34, vcc, s39, v152
	s_waitcnt lgkmcnt(0)
; template <int EPI>
; DI void gemm_phase(const P& p, int l, const u16* __restrict__ A, const u16* __restrict__ Bt, int mpx, char* lds) {
;     ...
;     for (int mi = 0; mi < 8; ++mi) {
;       float4 xv[4];
; #pragma unroll
;       for (int i = 0; i < 4; ++i) xv[i] = xn[i];
;       if (mi < 7) {
; #pragma unroll
;         for (int i = 0; i < 4; ++i) xn[i] = *(const float4*)(xr + (size_t)((mi + 1) * 16 + rr0 + 4 * i) * 1024 + c4);
;       }
; #pragma unroll
;       for (int ni = 0; ni < 4; ++ni)
; #pragma unroll
;         for (int j = 0; j < 4; ++j) Cw[(g * 4 + j) * 68 + ni * 16 + r] = acc[mi][ni][j];
;       __builtin_amdgcn_fence(__ATOMIC_RELEASE, "wavefront");
; #pragma unroll
;       for (int i = 0; i < 4; ++i) {
;         const int row = rr0 + 4 * i;
;         const float4 a = *(const float4*)&Cw[row * 68 + c4];
;         float4 z;
;         z.x = alpha * xv[i].x + gt.x * a.x;
;         z.y = alpha * xv[i].y + gt.y * a.y;
;         z.z = alpha * xv[i].z + gt.z * a.z;
;         z.w = alpha * xv[i].w + gt.w * a.w;
;         *(float4*)(Z + (size_t)(mi * 16 + row) * 1024 + c4) = z;
;       }
;       __builtin_amdgcn_fence(__ATOMIC_RELEASE, "wavefront");
;     ...
;   if (!has_next) break;
;   t = tn; m0 = m1; n0 = n1; Ag = Agn; Bg = Bgn;
	v_pk_mul_f32 v[14:15], v[18:19], v[14:15]
	v_pk_mul_f32 v[16:17], v[20:21], v[16:17]
	s_waitcnt vmcnt(11)
	v_pk_fma_f32 v[14:15], v[50:51], s[34:35], v[14:15] op_sel_hi:[1,0,1]
	v_pk_fma_f32 v[16:17], v[52:53], s[34:35], v[16:17] op_sel_hi:[1,0,1]
	v_addc_co_u32_e32 v35, vcc, 0, v153, vcc
	global_store_dwordx4 v[34:35], v[14:17], off
	ds_read_b128 v[14:17], v158
	v_add_co_u32_e32 v34, vcc, s39, v156
	s_waitcnt lgkmcnt(0)
	v_pk_mul_f32 v[14:15], v[18:19], v[14:15]
	v_pk_mul_f32 v[16:17], v[20:21], v[16:17]
	s_waitcnt vmcnt(11)
	v_pk_fma_f32 v[14:15], v[46:47], s[34:35], v[14:15] op_sel_hi:[1,0,1]
	v_pk_fma_f32 v[16:17], v[48:49], s[34:35], v[16:17] op_sel_hi:[1,0,1]
	v_addc_co_u32_e32 v35, vcc, 0, v157, vcc
	global_store_dwordx4 v[34:35], v[14:17], off
	ds_read_b128 v[14:17], v158 offset:1088
	v_add_co_u32_e32 v34, vcc, s39, v154
	s_waitcnt lgkmcnt(0)
	v_pk_mul_f32 v[14:15], v[18:19], v[14:15]
	v_pk_mul_f32 v[16:17], v[20:21], v[16:17]
	s_waitcnt vmcnt(11)
	v_pk_fma_f32 v[14:15], v[42:43], s[34:35], v[14:15] op_sel_hi:[1,0,1]
	v_pk_fma_f32 v[16:17], v[44:45], s[34:35], v[16:17] op_sel_hi:[1,0,1]
	v_addc_co_u32_e32 v35, vcc, 0, v155, vcc
	global_store_dwordx4 v[34:35], v[14:17], off
	ds_read_b128 v[14:17], v158 offset:2176
	v_add_co_u32_e32 v34, vcc, s39, v150
	s_waitcnt lgkmcnt(0)
	v_pk_mul_f32 v[14:15], v[18:19], v[14:15]
	v_pk_mul_f32 v[16:17], v[20:21], v[16:17]
	s_waitcnt vmcnt(11)
	v_pk_fma_f32 v[14:15], v[38:39], s[34:35], v[14:15] op_sel_hi:[1,0,1]
	v_pk_fma_f32 v[16:17], v[40:41], s[34:35], v[16:17] op_sel_hi:[1,0,1]
	v_addc_co_u32_e32 v35, vcc, 0, v151, vcc
	global_store_dwordx4 v[34:35], v[14:17], off
	ds_write2_b32 v165, v166, v170 offset1:16
	ds_write2_b32 v165, v167, v171 offset0:68 offset1:84
	ds_write2_b32 v165, v168, v172 offset0:136 offset1:152
	ds_write2_b32 v165, v169, v173 offset0:204 offset1:220
	ds_write2_b32 v165, v2, v6 offset0:32 offset1:48
	ds_write2_b32 v165, v3, v7 offset0:100 offset1:116
	ds_write2_b32 v165, v4, v8 offset0:168 offset1:184
	ds_write2_b32 v165, v5, v9 offset0:236 offset1:252
	ds_read_b128 v[2:5], v164
	v_add_co_u32_e32 v6, vcc, s46, v152
	s_waitcnt lgkmcnt(0)
	v_pk_mul_f32 v[2:3], v[18:19], v[2:3]
	v_pk_mul_f32 v[4:5], v[20:21], v[4:5]
	v_addc_co_u32_e32 v7, vcc, 0, v153, vcc
	s_waitcnt vmcnt(7)
	v_pk_fma_f32 v[2:3], v[10:11], s[34:35], v[2:3] op_sel_hi:[1,0,1]
	v_pk_fma_f32 v[4:5], v[12:13], s[34:35], v[4:5] op_sel_hi:[1,0,1]
	global_store_dwordx4 v[6:7], v[2:5], off
	ds_read_b128 v[2:5], v158
	v_add_co_u32_e32 v6, vcc, s46, v156
	s_waitcnt lgkmcnt(0)
	v_pk_mul_f32 v[2:3], v[18:19], v[2:3]
	v_pk_mul_f32 v[4:5], v[20:21], v[4:5]
	s_waitcnt vmcnt(7)
	v_pk_fma_f32 v[2:3], v[30:31], s[34:35], v[2:3] op_sel_hi:[1,0,1]
	v_pk_fma_f32 v[4:5], v[32:33], s[34:35], v[4:5] op_sel_hi:[1,0,1]
	v_addc_co_u32_e32 v7, vcc, 0, v157, vcc
	global_store_dwordx4 v[6:7], v[2:5], off
	ds_read_b128 v[2:5], v158 offset:1088
	v_add_co_u32_e32 v6, vcc, s46, v154
	s_mov_b64 s[46:47], s[44:45]
	s_nop 0
	v_addc_co_u32_e32 v7, vcc, 0, v155, vcc
	s_waitcnt lgkmcnt(0)
	v_pk_mul_f32 v[2:3], v[18:19], v[2:3]
	v_pk_mul_f32 v[4:5], v[20:21], v[4:5]
	s_waitcnt vmcnt(7)
	v_pk_fma_f32 v[2:3], v[26:27], s[34:35], v[2:3] op_sel_hi:[1,0,1]
	v_pk_fma_f32 v[4:5], v[28:29], s[34:35], v[4:5] op_sel_hi:[1,0,1]
	global_store_dwordx4 v[6:7], v[2:5], off
	ds_read_b128 v[2:5], v158 offset:2176
	v_add_co_u32_e32 v6, vcc, 0x70000, v150
	s_waitcnt lgkmcnt(0)
	v_pk_mul_f32 v[2:3], v[18:19], v[2:3]
	v_pk_mul_f32 v[4:5], v[20:21], v[4:5]
	v_addc_co_u32_e32 v7, vcc, 0, v151, vcc
	s_waitcnt vmcnt(7)
	v_pk_fma_f32 v[2:3], v[22:23], s[34:35], v[2:3] op_sel_hi:[1,0,1]
	v_pk_fma_f32 v[4:5], v[24:25], s[34:35], v[4:5] op_sel_hi:[1,0,1]
	s_and_b64 vcc, exec, s[40:41]
	global_store_dwordx4 v[6:7], v[2:5], off
	s_cbranch_vccz .LBB0_69
	v_mov_b32_e32 v236, 0x358637bd
